# P3: workgroups with blockIdx bit3 set run gMLP-gate items before RWKV-prep items (de-phase HBM bursts); control flow only
# speedup vs baseline: 1.0018x; 1.0018x over previous
; __device__ __forceinline__ float bf_lo(unsigned u) { return __uint_as_float(u << 16); }
; __device__ __forceinline__ float bf_hi(unsigned u) { return __uint_as_float(u & 0xffff0000u); }
; __device__ __forceinline__ unsigned pk2(float lo, float hi) { return pg8::cvt_pk_bf16(lo, hi); }
; __device__ __forceinline__ float sigmoid1(float x) { return __builtin_amdgcn_rcpf(1.0f + __expf(-x)); }
; __device__ __forceinline__ float tanh_fast(float x) { const float e = __expf(-2.0f * fabsf(x)); const float t = (1.0f - e) * __builtin_amdgcn_rcpf(1.0f + e); return x < 0.f ? -t : t; }
; __global__ void __launch_bounds__(NT, 2) mk_fwd(Args args) {
;     ...
;     if (IN(3)) REPS(3) {
;         for (int item_ = bx; item_ < 256 * RMUL(3); item_ += G) {
;             const int item = item_ & 255;
;             __syncthreads();
;             {
;                 const int t0 = item * 64;
;                 bf16* Al = (bf16*)lds;
;                 bf16* Ks = (bf16*)(lds + 40960);
;                 const float* mu = args.in[11];
;                 {
;                     const int tl = tid >> 3, cb = (tid & 7) * 36; const int t = t0 + tl; const bool first = (t & (SEQ - 1)) == 0;
;                     const bf16* cur = P + (size_t)t * NINP + 2048 + 3072 + cb; const bf16* prv = cur - NINP;
; #pragma unroll 6
;                     for (int q = 0; q < 18; ++q) { const unsigned c2 = *(const unsigned*)(cur + 2 * q); const unsigned p2 = first ? 0u : *(const unsigned*)(prv + 2 * q);
;                         const int c = cb + 2 * q; const float m0 = mu[3072 + c], m1 = mu[3072 + c + 1];
;                         float v0 = bf_lo(c2), v1 = bf_hi(c2); v0 += (bf_lo(p2) - v0) * m0; v1 += (bf_hi(p2) - v1) * m1;
;                         if (c < 64) { v0 = tanh_fast(v0); v1 = tanh_fast(v1); } else if (c >= 128) { v0 = sigmoid1(v0); v1 = sigmoid1(v1); }
;                         *(unsigned*)(Al + tl * 296 + c) = pk2(v0, v1); }
;                 }
.LBB0_300:
	s_cmp_lt_i32 s94, 4
	s_cselect_b64 s[6:7], -1, 0
	s_add_u32 s96, s92, 0x19a00000
	s_addc_u32 s97, s93, 0
	s_add_u32 s30, s92, 0x1ba00000
	s_addc_u32 s31, s93, 0
	s_add_u32 s34, s92, 0x1da00000
	s_addc_u32 s35, s93, 0
	s_add_u32 s24, s92, 0x1fa00000
	s_addc_u32 s25, s93, 0
	s_add_u32 s26, s90, 0x4000000
	s_addc_u32 s27, s91, 0
	s_add_u32 s28, s90, 0x6000000
	s_addc_u32 s29, s91, 0
	s_and_b64 s[40:41], s[6:7], s[0:1]
	s_cmpk_lt_i32 s2, 0x100
	s_cselect_b64 s[38:39], -1, 0
	s_and_b64 s[0:1], s[40:41], s[38:39]
	s_andn2_b64 vcc, exec, s[0:1]
	s_cbranch_vccnz .LBB0_389
	s_mov_b32 s101, 0
	s_bitcmp1_b32 s2, 3
	s_cbranch_scc0 .Lp3_preA
	v_writelane_b32 v249, s68, 31
	v_writelane_b32 v249, s69, 32
	s_lshl_b32 s3, s85, 7
	v_and_b32_e32 v129, 31, v168
	v_lshrrev_b32_e32 v131, 3, v168
	v_lshrrev_b32_e32 v135, 2, v168
	v_mbcnt_hi_u32_b32 v208, -1, v169
	v_and_b32_e32 v131, 4, v131
	v_and_b32_e32 v117, 64, v208
	v_xor_b32_e32 v137, 16, v208
	v_add_u32_e32 v117, 64, v117
	s_mov_b32 s98, s58
	s_mov_b32 s99, s59
	v_cmp_lt_i32_e32 vcc, v137, v117
	s_mov_b32 s100, s60
	s_mov_b32 s101, 1
	v_cndmask_b32_e32 v137, v208, v137, vcc
	v_lshlrev_b32_e32 v137, 2, v137
	s_branch .Lp3_preB
.Lp3_preA:
	v_writelane_b32 v249, s68, 31
	s_lshl_b32 s3, s85, 7
	v_and_b32_e32 v129, 31, v168
	v_writelane_b32 v249, s69, 32
	v_or_b32_e32 v64, s3, v129
	v_lshrrev_b32_e32 v133, 3, v168
	v_lshrrev_b32_e32 v0, 1, v168
	v_ashrrev_i32_e32 v65, 31, v64
	v_readlane_b32 s4, v249, 8
	v_and_b32_e32 v5, 16, v0
	v_and_b32_e32 v131, 4, v133
	v_lshlrev_b64 v[0:1], 2, v[64:65]
	v_readlane_b32 s6, v249, 10
	v_readlane_b32 s7, v249, 11
	v_readlane_b32 s8, v249, 12
	v_readlane_b32 s9, v249, 13
	v_or_b32_e32 v72, 0x60, v64
	v_lshl_add_u64 v[74:75], s[60:61], 0, v[0:1]
	v_lshl_add_u64 v[76:77], s[90:91], 0, v[0:1]
	v_lshl_add_u64 v[78:79], s[64:65], 0, v[0:1]
	v_lshl_add_u64 v[80:81], s[6:7], 0, v[0:1]
	v_lshl_add_u64 v[82:83], s[8:9], 0, v[0:1]
	v_mul_u32_u24_e32 v1, 0x408, v131
	v_ashrrev_i32_e32 v73, 31, v72
	v_lshlrev_b32_e32 v0, 1, v64
	v_lshlrev_b32_e32 v1, 1, v1
	v_or_b32_e32 v70, 64, v64
	v_add3_u32 v171, 0, v0, v1
	v_lshlrev_b64 v[0:1], 7, v[72:73]
	v_ashrrev_i32_e32 v71, 31, v70
	v_or_b32_e32 v0, v0, v5
	v_or_b32_e32 v68, 32, v64
	v_lshl_add_u64 v[100:101], s[92:93], 0, v[0:1]
	v_lshlrev_b64 v[0:1], 7, v[70:71]
	v_ashrrev_i32_e32 v69, 31, v68
	v_or_b32_e32 v0, v0, v5
	v_lshl_add_u64 v[102:103], s[92:93], 0, v[0:1]
	v_lshlrev_b64 v[0:1], 7, v[68:69]
	s_mov_b64 s[0:1], 0x80
	v_or_b32_e32 v0, v0, v5
	v_lshl_add_u64 v[84:85], v[76:77], 0, s[0:1]
	s_mov_b64 s[0:1], 0x100
	v_lshl_add_u64 v[104:105], s[92:93], 0, v[0:1]
	v_lshlrev_b64 v[0:1], 7, v[64:65]
	v_lshl_add_u64 v[86:87], v[76:77], 0, s[0:1]
	s_mov_b64 s[0:1], 0x180
	v_or_b32_e32 v0, v0, v5
	s_movk_i32 s6, 0x140
	v_lshl_add_u64 v[88:89], v[76:77], 0, s[0:1]
	v_lshl_add_u64 v[106:107], s[92:93], 0, v[0:1]
	v_mad_i64_i32 v[0:1], s[0:1], v72, s6, 0
	v_or_b32_e32 v0, v0, v5
	v_lshl_add_u64 v[108:109], s[92:93], 0, v[0:1]
	v_mad_i64_i32 v[0:1], s[0:1], v70, s6, 0
	v_or_b32_e32 v0, v0, v5
	v_lshl_add_u64 v[110:111], s[92:93], 0, v[0:1]
	v_mad_i64_i32 v[0:1], s[0:1], v68, s6, 0
	v_and_b32_e32 v2, 7, v168
	v_or_b32_e32 v0, v0, v5
	v_mul_u32_u24_e32 v3, 36, v2
	v_lshl_add_u64 v[112:113], s[92:93], 0, v[0:1]
	v_mad_i64_i32 v[0:1], s[0:1], v64, s6, 0
	v_mul_u32_u24_e32 v4, 0x250, v133
	v_add_u32_e32 v170, 0, v5
	v_lshlrev_b32_e32 v96, 1, v3
	v_mov_b32_e32 v97, 0
	v_or_b32_e32 v0, v0, v5
	s_movk_i32 s46, 0x250
	v_lshrrev_b32_e32 v135, 2, v168
	v_lshl_add_u64 v[66:67], v[64:65], 1, s[26:27]
	v_or_b32_e32 v172, 1, v131
	v_add_u32_e32 v173, 0x810, v171
	v_or_b32_e32 v174, 2, v131
	v_add_u32_e32 v175, 0x1020, v171
	v_or_b32_e32 v176, 3, v131
	v_add_u32_e32 v177, 0x1830, v171
	v_or_b32_e32 v178, 8, v131
	v_add_u32_e32 v179, 0x4080, v171
	v_or_b32_e32 v180, 9, v131
	v_add_u32_e32 v181, 0x4890, v171
	v_or_b32_e32 v182, 10, v131
	v_add_u32_e32 v183, 0x50a0, v171
	v_or_b32_e32 v184, 11, v131
	v_add_u32_e32 v185, 0x58b0, v171
	v_or_b32_e32 v186, 16, v131
	v_add_u32_e32 v187, 0x8100, v171
	v_or_b32_e32 v188, 17, v131
	v_add_u32_e32 v189, 0x8910, v171
	v_or_b32_e32 v190, 18, v131
	v_add_u32_e32 v191, 0x9120, v171
	v_or_b32_e32 v192, 19, v131
	v_add_u32_e32 v193, 0x9930, v171
	v_or_b32_e32 v194, 24, v131
	v_add_u32_e32 v195, 0xc180, v171
	v_or_b32_e32 v196, 25, v131
	v_add_u32_e32 v197, 0xc990, v171
	v_or_b32_e32 v198, 26, v131
	v_add_u32_e32 v199, 0xd1a0, v171
	v_or_b32_e32 v200, 27, v131
	v_add_u32_e32 v201, 0xd9b0, v171
	v_lshl_add_u64 v[90:91], v[68:69], 1, s[26:27]
	v_lshl_add_u64 v[92:93], v[70:71], 1, s[26:27]
	v_lshl_add_u64 v[94:95], v[72:73], 1, s[26:27]
	v_lshl_add_u64 v[98:99], s[92:93], 0, v[96:97]
	v_mad_u32_u24 v202, v2, 36, 10
	v_add3_u32 v203, v4, v96, 0
	v_lshrrev_b32_e32 v204, 7, v168
	v_lshlrev_b32_e32 v205, 3, v168
	v_add_u32_e32 v206, 0x80, v170
	v_add_u32_e32 v207, 0x100, v170
	v_lshl_add_u64 v[114:115], s[92:93], 0, v[0:1]
	s_movk_i32 s47, 0x7ff
	s_movk_i32 s60, 0x7f
	s_movk_i32 s61, 0x2c00
	s_mov_b64 s[6:7], 0x1000
	s_movk_i32 s62, 0xfff
	s_movk_i32 s63, 0x2dff
	s_mov_b32 s64, 0x280000
	s_mov_b32 s65, 0x2a0000
	s_mov_b32 s66, 0x2c0000
	v_mbcnt_hi_u32_b32 v208, -1, v169
	s_mov_b32 s67, s2
	v_readlane_b32 s5, v249, 9
	v_readlane_b32 s10, v249, 14
	v_readlane_b32 s11, v249, 15
	v_readlane_b32 s12, v249, 16
	v_readlane_b32 s13, v249, 17
	v_readlane_b32 s14, v249, 18
	v_readlane_b32 s15, v249, 19
	v_readlane_b32 s16, v249, 20
	v_readlane_b32 s17, v249, 21
	v_readlane_b32 s18, v249, 22
	v_readlane_b32 s19, v249, 23

; __device__ __forceinline__ bf16 f2bf(float f) { return (bf16)(pg8::cvt_pk_bf16(f, 0.f) & 0xffffu); }
; #define RW_ZERO() do { _Pragma("unroll") for (int b_ = 0; b_ < 4; ++b_) _Pragma("unroll") for (int r_ = 0; r_ < 16; ++r_) acc[b_][r_] = 0.f; } while (0)
; __global__ void __launch_bounds__(NT, 2) mk_fwd(Args args) {
;     ...
;                     RW_ZERO(); RW_MM(G2T, 160, 128, 10);
; #pragma unroll
;                     for (int nt = 0; nt < 4; ++nt) { const int col = c0 + nt * 32 + (lane & 31);
; #pragma unroll
;                         for (int r = 0; r < 16; ++r) { const int t = t0 + mt * 32 + (r & 3) + 8 * (r >> 2) + 4 * (lane >> 5);
;                             GG[(size_t)t * 1024 + col] = f2bf(acc[nt][r]); }
;                         asm volatile("" ::: "memory"); }
.LBB0_370:
	v_lshl_add_u64 v[160:161], v[114:115], 0, s[8:9]
	v_add_co_u32_e32 v218, vcc, s66, v160
	v_lshl_add_u64 v[162:163], v[112:113], 0, s[8:9]
	s_nop 0
	v_addc_co_u32_e32 v219, vcc, 0, v161, vcc
	v_add_co_u32_e32 v222, vcc, s66, v162
	v_lshl_add_u64 v[164:165], v[110:111], 0, s[8:9]
	s_nop 0
	v_addc_co_u32_e32 v223, vcc, 0, v163, vcc
	v_add_co_u32_e32 v224, vcc, s66, v164
	v_lshl_add_u64 v[166:167], v[108:109], 0, s[8:9]
	s_nop 0
	v_addc_co_u32_e32 v225, vcc, 0, v165, vcc
	v_add_co_u32_e32 v226, vcc, s66, v166
	ds_read_b128 v[152:155], v119
	ds_read_b128 v[156:159], v119 offset:32
	v_addc_co_u32_e32 v227, vcc, 0, v167, vcc
	global_load_dwordx4 v[160:163], v[218:219], off
	global_load_dwordx4 v[164:167], v[222:223], off
	global_load_dwordx4 v[210:213], v[224:225], off
	global_load_dwordx4 v[214:217], v[226:227], off
	s_nop 0
	global_load_dwordx4 v[218:221], v[218:219], off offset:32
	s_add_u32 s8, s8, 64
	s_addc_u32 s9, s9, 0
	s_cmpk_eq_i32 s8, 0x140
	v_add_u32_e32 v119, 64, v119
	s_waitcnt vmcnt(4) lgkmcnt(1)
	v_mfma_f32_32x32x16_bf16 v[48:63], v[152:155], v[160:163], v[48:63]
	global_load_dwordx4 v[160:163], v[222:223], off offset:32
	s_waitcnt vmcnt(4)
	v_mfma_f32_32x32x16_bf16 v[32:47], v[152:155], v[164:167], v[32:47]
	global_load_dwordx4 v[164:167], v[224:225], off offset:32
	s_waitcnt vmcnt(4)
	v_mfma_f32_32x32x16_bf16 v[16:31], v[152:155], v[210:213], v[16:31]
	global_load_dwordx4 v[210:213], v[226:227], off offset:32
	s_waitcnt vmcnt(4)
	v_mfma_f32_32x32x16_bf16 v[0:15], v[152:155], v[214:217], v[0:15]
	s_waitcnt vmcnt(3) lgkmcnt(0)
	v_mfma_f32_32x32x16_bf16 v[48:63], v[156:159], v[218:221], v[48:63]
	s_waitcnt vmcnt(2)
	v_mfma_f32_32x32x16_bf16 v[32:47], v[156:159], v[160:163], v[32:47]
	s_waitcnt vmcnt(1)
	v_mfma_f32_32x32x16_bf16 v[16:31], v[156:159], v[164:167], v[16:31]
	s_waitcnt vmcnt(0)
	v_mfma_f32_32x32x16_bf16 v[0:15], v[156:159], v[210:213], v[0:15]
	s_cbranch_scc0 .LBB0_370
	v_lshlrev_b32_e32 v96, 1, v96
	v_cvt_pk_bf16_f32 v48, v48, v97
	v_lshl_add_u64 v[152:153], v[66:67], 0, v[96:97]
	s_nop 2
	global_store_short v[152:153], v48, off
	v_cvt_pk_bf16_f32 v48, v49, v97
	global_store_short v[152:153], v48, off offset:2048
	v_lshlrev_b32_e32 v48, 1, v116
	v_mov_b32_e32 v49, v97
	v_cvt_pk_bf16_f32 v50, v50, v97
	v_lshl_add_u64 v[152:153], v[66:67], 0, v[48:49]
	global_store_short v[152:153], v50, off
	v_cvt_pk_bf16_f32 v116, v51, v97
	v_lshlrev_b32_e32 v50, 1, v118
	v_mov_b32_e32 v51, v97
	v_lshl_add_u64 v[118:119], v[66:67], 0, v[50:51]
	global_store_short v[118:119], v116, off
	v_lshlrev_b32_e32 v118, 1, v120
	v_mov_b32_e32 v119, v97
	v_cvt_pk_bf16_f32 v52, v52, v97
	v_lshl_add_u64 v[120:121], v[66:67], 0, v[118:119]
	global_store_short v[120:121], v52, off
	v_cvt_pk_bf16_f32 v116, v53, v97
	v_lshlrev_b32_e32 v52, 1, v122
	v_mov_b32_e32 v53, v97
	v_lshl_add_u64 v[120:121], v[66:67], 0, v[52:53]
	global_store_short v[120:121], v116, off
	v_lshlrev_b32_e32 v120, 1, v124
	v_mov_b32_e32 v121, v97
	v_cvt_pk_bf16_f32 v54, v54, v97
	v_lshl_add_u64 v[122:123], v[66:67], 0, v[120:121]
	global_store_short v[122:123], v54, off
	v_cvt_pk_bf16_f32 v116, v55, v97
	v_lshlrev_b32_e32 v54, 1, v126
	v_mov_b32_e32 v55, v97
	v_lshl_add_u64 v[122:123], v[66:67], 0, v[54:55]
	global_store_short v[122:123], v116, off
	v_lshlrev_b32_e32 v122, 1, v136
	v_mov_b32_e32 v123, v97
	v_cvt_pk_bf16_f32 v56, v56, v97
	v_lshl_add_u64 v[124:125], v[66:67], 0, v[122:123]
	global_store_short v[124:125], v56, off
	v_cvt_pk_bf16_f32 v116, v57, v97
	v_lshlrev_b32_e32 v56, 1, v138
	v_mov_b32_e32 v57, v97
	v_lshl_add_u64 v[124:125], v[66:67], 0, v[56:57]
	global_store_short v[124:125], v116, off
	v_lshlrev_b32_e32 v124, 1, v140
	v_mov_b32_e32 v125, v97
	v_cvt_pk_bf16_f32 v58, v58, v97
	v_lshl_add_u64 v[126:127], v[66:67], 0, v[124:125]
	global_store_short v[126:127], v58, off
	v_cvt_pk_bf16_f32 v116, v59, v97
	v_lshlrev_b32_e32 v58, 1, v142
	v_mov_b32_e32 v59, v97
	v_lshl_add_u64 v[126:127], v[66:67], 0, v[58:59]
	global_store_short v[126:127], v116, off
	v_lshlrev_b32_e32 v126, 1, v144
	v_mov_b32_e32 v127, v97
	v_cvt_pk_bf16_f32 v60, v60, v97
	v_lshl_add_u64 v[138:139], v[66:67], 0, v[126:127]
	global_store_short v[138:139], v60, off
	v_cvt_pk_bf16_f32 v116, v61, v97
	v_lshlrev_b32_e32 v60, 1, v146
	v_mov_b32_e32 v61, v97
	v_lshl_add_u64 v[138:139], v[66:67], 0, v[60:61]
	global_store_short v[138:139], v116, off
	v_lshlrev_b32_e32 v138, 1, v148
	v_mov_b32_e32 v139, v97
	v_cvt_pk_bf16_f32 v62, v62, v97
	v_lshl_add_u64 v[140:141], v[66:67], 0, v[138:139]
	global_store_short v[140:141], v62, off
	v_cvt_pk_bf16_f32 v116, v63, v97
	v_lshlrev_b32_e32 v62, 1, v150
	v_mov_b32_e32 v63, v97
	v_lshl_add_u64 v[140:141], v[66:67], 0, v[62:63]
	global_store_short v[140:141], v116, off
	v_lshl_add_u64 v[140:141], s[26:27], 0, v[96:97]
	v_cvt_pk_bf16_f32 v32, v32, v97
	v_lshl_add_u64 v[142:143], v[68:69], 1, v[140:141]
	global_store_short v[142:143], v32, off
	v_cvt_pk_bf16_f32 v116, v33, v97
	v_lshl_add_u64 v[32:33], v[90:91], 0, v[96:97]
	global_store_short v[32:33], v116, off offset:2048
	v_lshl_add_u64 v[32:33], v[90:91], 0, v[48:49]
	v_cvt_pk_bf16_f32 v34, v34, v97
	global_store_short v[32:33], v34, off
	v_lshl_add_u64 v[32:33], v[90:91], 0, v[50:51]
	v_cvt_pk_bf16_f32 v34, v35, v97
	global_store_short v[32:33], v34, off
	v_lshl_add_u64 v[32:33], v[90:91], 0, v[118:119]
	v_cvt_pk_bf16_f32 v34, v36, v97
	global_store_short v[32:33], v34, off
	v_lshl_add_u64 v[32:33], v[90:91], 0, v[52:53]
	v_cvt_pk_bf16_f32 v34, v37, v97
	global_store_short v[32:33], v34, off
	v_lshl_add_u64 v[32:33], v[90:91], 0, v[120:121]
	v_cvt_pk_bf16_f32 v34, v38, v97
	global_store_short v[32:33], v34, off
; __device__ __forceinline__ bf16 f2bf(float f) { return (bf16)(pg8::cvt_pk_bf16(f, 0.f) & 0xffffu); }
; __global__ void __launch_bounds__(NT, 2) mk_fwd(Args args) {
;     ...
;                     for (int nt = 0; nt < 4; ++nt) { const int col = c0 + nt * 32 + (lane & 31);
; #pragma unroll
;                         for (int r = 0; r < 16; ++r) { const int t = t0 + mt * 32 + (r & 3) + 8 * (r >> 2) + 4 * (lane >> 5);
;                             GG[(size_t)t * 1024 + col] = f2bf(acc[nt][r]); }
;                         asm volatile("" ::: "memory"); }
;                 }
;             }
;         }
;     ...
;         for (int item_ = bx; item_ < 256 * RMUL(3); item_ += G) {
	v_lshl_add_u64 v[32:33], v[90:91], 0, v[54:55]
	v_cvt_pk_bf16_f32 v34, v39, v97
	global_store_short v[32:33], v34, off
	v_lshl_add_u64 v[32:33], v[90:91], 0, v[122:123]
	v_cvt_pk_bf16_f32 v34, v40, v97
	global_store_short v[32:33], v34, off
	v_lshl_add_u64 v[32:33], v[90:91], 0, v[56:57]
	v_cvt_pk_bf16_f32 v34, v41, v97
	global_store_short v[32:33], v34, off
	v_lshl_add_u64 v[32:33], v[90:91], 0, v[124:125]
	v_cvt_pk_bf16_f32 v34, v42, v97
	global_store_short v[32:33], v34, off
	v_lshl_add_u64 v[32:33], v[90:91], 0, v[58:59]
	v_cvt_pk_bf16_f32 v34, v43, v97
	global_store_short v[32:33], v34, off
	v_lshl_add_u64 v[32:33], v[90:91], 0, v[126:127]
	v_cvt_pk_bf16_f32 v34, v44, v97
	global_store_short v[32:33], v34, off
	v_lshl_add_u64 v[32:33], v[90:91], 0, v[60:61]
	v_cvt_pk_bf16_f32 v34, v45, v97
	global_store_short v[32:33], v34, off
	v_lshl_add_u64 v[32:33], v[90:91], 0, v[138:139]
	v_cvt_pk_bf16_f32 v34, v46, v97
	global_store_short v[32:33], v34, off
	v_lshl_add_u64 v[32:33], v[90:91], 0, v[62:63]
	v_cvt_pk_bf16_f32 v34, v47, v97
	global_store_short v[32:33], v34, off
	v_cvt_pk_bf16_f32 v16, v16, v97
	v_lshl_add_u64 v[32:33], v[70:71], 1, v[140:141]
	global_store_short v[32:33], v16, off
	v_cvt_pk_bf16_f32 v32, v17, v97
	v_lshl_add_u64 v[16:17], v[92:93], 0, v[96:97]
	global_store_short v[16:17], v32, off offset:2048
	v_lshl_add_u64 v[16:17], v[92:93], 0, v[48:49]
	v_cvt_pk_bf16_f32 v18, v18, v97
	global_store_short v[16:17], v18, off
	v_lshl_add_u64 v[16:17], v[92:93], 0, v[50:51]
	v_cvt_pk_bf16_f32 v18, v19, v97
	global_store_short v[16:17], v18, off
	v_lshl_add_u64 v[16:17], v[92:93], 0, v[118:119]
	v_cvt_pk_bf16_f32 v18, v20, v97
	global_store_short v[16:17], v18, off
	v_lshl_add_u64 v[16:17], v[92:93], 0, v[52:53]
	v_cvt_pk_bf16_f32 v18, v21, v97
	global_store_short v[16:17], v18, off
	v_lshl_add_u64 v[16:17], v[92:93], 0, v[120:121]
	v_cvt_pk_bf16_f32 v18, v22, v97
	global_store_short v[16:17], v18, off
	v_lshl_add_u64 v[16:17], v[92:93], 0, v[54:55]
	v_cvt_pk_bf16_f32 v18, v23, v97
	global_store_short v[16:17], v18, off
	v_lshl_add_u64 v[16:17], v[92:93], 0, v[122:123]
	v_cvt_pk_bf16_f32 v18, v24, v97
	global_store_short v[16:17], v18, off
	v_lshl_add_u64 v[16:17], v[92:93], 0, v[56:57]
	v_cvt_pk_bf16_f32 v18, v25, v97
	global_store_short v[16:17], v18, off
	v_lshl_add_u64 v[16:17], v[92:93], 0, v[124:125]
	v_cvt_pk_bf16_f32 v18, v26, v97
	global_store_short v[16:17], v18, off
	v_lshl_add_u64 v[16:17], v[92:93], 0, v[58:59]
	v_cvt_pk_bf16_f32 v18, v27, v97
	global_store_short v[16:17], v18, off
	v_lshl_add_u64 v[16:17], v[92:93], 0, v[126:127]
	v_cvt_pk_bf16_f32 v18, v28, v97
	global_store_short v[16:17], v18, off
	v_lshl_add_u64 v[16:17], v[92:93], 0, v[60:61]
	v_cvt_pk_bf16_f32 v18, v29, v97
	global_store_short v[16:17], v18, off
	v_lshl_add_u64 v[16:17], v[92:93], 0, v[138:139]
	v_cvt_pk_bf16_f32 v18, v30, v97
	global_store_short v[16:17], v18, off
	v_lshl_add_u64 v[16:17], v[92:93], 0, v[62:63]
	v_cvt_pk_bf16_f32 v18, v31, v97
	global_store_short v[16:17], v18, off
	v_cvt_pk_bf16_f32 v0, v0, v97
	v_lshl_add_u64 v[16:17], v[72:73], 1, v[140:141]
	global_store_short v[16:17], v0, off
	v_cvt_pk_bf16_f32 v16, v1, v97
	v_lshl_add_u64 v[0:1], v[94:95], 0, v[96:97]
	global_store_short v[0:1], v16, off offset:2048
	v_lshl_add_u64 v[0:1], v[94:95], 0, v[48:49]
	v_cvt_pk_bf16_f32 v2, v2, v97
	global_store_short v[0:1], v2, off
	v_lshl_add_u64 v[0:1], v[94:95], 0, v[50:51]
	v_cvt_pk_bf16_f32 v2, v3, v97
	global_store_short v[0:1], v2, off
	v_lshl_add_u64 v[0:1], v[94:95], 0, v[118:119]
	v_cvt_pk_bf16_f32 v2, v4, v97
	global_store_short v[0:1], v2, off
	v_lshl_add_u64 v[0:1], v[94:95], 0, v[52:53]
	v_cvt_pk_bf16_f32 v2, v5, v97
	global_store_short v[0:1], v2, off
	v_lshl_add_u64 v[0:1], v[94:95], 0, v[120:121]
	v_cvt_pk_bf16_f32 v2, v6, v97
	global_store_short v[0:1], v2, off
	v_lshl_add_u64 v[0:1], v[94:95], 0, v[54:55]
	v_cvt_pk_bf16_f32 v2, v7, v97
	global_store_short v[0:1], v2, off
	v_lshl_add_u64 v[0:1], v[94:95], 0, v[122:123]
	v_cvt_pk_bf16_f32 v2, v8, v97
	global_store_short v[0:1], v2, off
	v_lshl_add_u64 v[0:1], v[94:95], 0, v[56:57]
	v_cvt_pk_bf16_f32 v2, v9, v97
	global_store_short v[0:1], v2, off
	v_lshl_add_u64 v[0:1], v[94:95], 0, v[124:125]
	v_cvt_pk_bf16_f32 v2, v10, v97
	global_store_short v[0:1], v2, off
	v_lshl_add_u64 v[0:1], v[94:95], 0, v[58:59]
	v_cvt_pk_bf16_f32 v2, v11, v97
	global_store_short v[0:1], v2, off
	v_lshl_add_u64 v[0:1], v[94:95], 0, v[126:127]
	v_cvt_pk_bf16_f32 v2, v12, v97
	global_store_short v[0:1], v2, off
	v_lshl_add_u64 v[0:1], v[94:95], 0, v[60:61]
	v_cvt_pk_bf16_f32 v2, v13, v97
	global_store_short v[0:1], v2, off
	v_lshl_add_u64 v[0:1], v[94:95], 0, v[138:139]
	v_cvt_pk_bf16_f32 v2, v14, v97
	global_store_short v[0:1], v2, off
	v_lshl_add_u64 v[0:1], v[94:95], 0, v[62:63]
	v_cvt_pk_bf16_f32 v2, v15, v97
	global_store_short v[0:1], v2, off
	s_mov_b32 s69, 32
	s_mov_b64 s[8:9], 0
	s_and_b64 vcc, exec, s[0:1]
	s_cbranch_vccz .LBB0_353
	s_add_i32 s67, s67, s84
	s_cmpk_gt_i32 s67, 0xff
	s_cbranch_scc0 .LBB0_302
	s_cmp_eq_u32 s101, 2
	s_cbranch_scc0 .Lp3_preB
	v_readlane_b32 s68, v249, 31
	v_readlane_b32 s69, v249, 32
	s_branch .LBB0_389
; __device__ __forceinline__ float bf_lo(unsigned u) { return __uint_as_float(u << 16); }
; __device__ __forceinline__ float bf_hi(unsigned u) { return __uint_as_float(u & 0xffff0000u); }
; __device__ __forceinline__ float wave_sum(float v) { v = row16_sum(v); v += __shfl_xor(v, 16); v += __shfl_xor(v, 32); return v; }
; __global__ void __launch_bounds__(NT, 2) mk_fwd(Args args) {
;     ...
;         for (int item_ = bx; item_ < 256 * RMUL(3); item_ += G) {
;             const int item = item_ & 255;
;             __syncthreads();
;             {
;                 const int T0 = (item >> 1) * 128, hg = (item & 1) * 4;
;                 bf16* VnT = (bf16*)lds;
;                 f32x2* st = (f32x2*)(lds + 36864);
;                 const float* vg = args.in[6]; const float* vb = args.in[7]; const float* wsp = args.in[8]; const float* bs = args.in[9];
; #pragma unroll 1
;                 for (int i0 = 0; i0 < 16; i0 += 4) {
;                     u32x4 a[4], b[4];
; #pragma unroll
;                     for (int i = 0; i < 4; ++i) { const bf16* row = P + (size_t)(T0 + wave * 16 + i0 + i) * NINP + 1024; a[i] = *(const u32x4*)(row + lane * 8); b[i] = *(const u32x4*)(row + 512 + lane * 8); }
; #pragma unroll
;                     for (int i = 0; i < 4; ++i) { float s = 0.f, s2 = 0.f;
; #pragma unroll
;                         for (int q = 0; q < 4; ++q) { const float v0 = bf_lo(a[i][q]), v1 = bf_hi(a[i][q]), v2 = bf_lo(b[i][q]), v3 = bf_hi(b[i][q]); s += (v0 + v1) + (v2 + v3); s2 += (v0 * v0 + v1 * v1) + (v2 * v2 + v3 * v3); }
;                         s = wave_sum(s); s2 = wave_sum(s2);
;                         const float mean = s * (1.0f / 1024.0f); const float var = fmaxf(s2 * (1.0f / 1024.0f) - mean * mean, 0.f);
;                         if (lane == 0) st[wave * 16 + i0 + i] = (f32x2){mean, rsqrtf(var + 1e-5f)}; }
;                 }
;                 for (int hh = 0; hh < 4; ++hh) {
;                     const int h = hg + hh;
;                     __syncthreads();
;                     {
;                         const int j = tid >> 2, d0 = (tid & 3) * 32; const f32x2 sj = st[j];
.Lp3_preB:
	v_xor_b32_e32 v0, 32, v208
	s_lshl_b32 s6, s85, 4
	v_cmp_lt_i32_e32 vcc, v0, v117
	s_ashr_i32 s8, s85, 1
	s_cmp_lt_i32 s8, 2
	v_cndmask_b32_e32 v0, v208, v0, vcc
	v_lshlrev_b32_e32 v141, 2, v0
	v_lshlrev_b32_e32 v0, 5, v168
	s_cselect_b32 s9, 4, 8
	s_lshl_b32 s8, s8, 5
	v_lshrrev_b32_e32 v2, 5, v128
	v_and_b32_e32 v145, 0x60, v0
	v_or_b32_e32 v153, s8, v131
	s_ashr_i32 s10, s8, 31
	v_or_b32_e32 v32, s8, v129
	v_lshl_or_b32 v158, v2, 2, s8
	s_lshl_b32 s8, s85, 6
	s_add_i32 s3, s3, 0
	v_mul_u32_u24_e32 v1, 0x88, v145
	v_and_or_b32 v38, s8, 64, v129
	s_add_i32 s3, s3, 0x9000
	s_mul_i32 s8, s85, 0x2c000
	v_lshl_add_u32 v149, v135, 3, 0
	v_mul_i32_i24_e32 v0, -6, v135
	v_mov_b32_e32 v33, s10
	v_mov_b32_e32 v35, 0
	v_lshlrev_b32_e32 v1, 1, v1
	s_mul_hi_i32 s6, s6, 0x2c00
	s_add_u32 s10, s92, s8
	v_and_b32_e32 v34, 32, v128
	v_add3_u32 v159, v149, v0, v1
	v_lshlrev_b32_e32 v0, 1, v135
	v_mov_b32_e32 v131, v35
	s_addc_u32 s11, s93, s6
	v_lshl_add_u64 v[36:37], s[52:53], 0, v[34:35]
	v_add3_u32 v160, 0, v1, v0
	v_lshlrev_b32_e32 v34, 1, v145
	v_lshl_add_u64 v[0:1], s[10:11], 0, v[130:131]
	s_mov_b64 s[10:11], 0xea09000
	v_mul_u32_u24_e32 v3, 0x110, v38
	v_lshl_add_u64 v[42:43], s[20:21], 0, v[34:35]
	v_lshlrev_b32_e32 v34, 1, v38
	v_lshl_add_u64 v[46:47], v[0:1], 0, s[10:11]
	v_lshlrev_b32_e32 v0, 4, v2
	v_readlane_b32 s68, v249, 31
	s_mov_b32 s7, 0
	v_cmp_eq_u32_e64 s[0:1], 0, v128
	v_add_u32_e32 v161, 0x220, v160
	v_add_u32_e32 v162, 0x440, v160
	v_add_u32_e32 v163, 0x660, v160
	v_add_u32_e32 v164, 0x880, v160
	v_add_u32_e32 v165, 0xaa0, v160
	v_add_u32_e32 v166, 0xcc0, v160
	v_add_u32_e32 v167, 0xee0, v160
	v_add_u32_e32 v170, 0x1100, v160
	v_add_u32_e32 v171, 0x1320, v160
	v_add_u32_e32 v172, 0x1540, v160
	v_add_u32_e32 v173, 0x1760, v160
	v_add_u32_e32 v174, 0x1980, v160
	v_add_u32_e32 v175, 0x1ba0, v160
	v_add_u32_e32 v176, 0x1dc0, v160
	v_add_u32_e32 v177, 0x1fe0, v159
	v_add_u32_e32 v178, 0x1fe0, v160
	v_or_b32_e32 v40, 32, v38
	v_or_b32_e32 v179, 1, v158
	v_or_b32_e32 v180, 2, v158
	v_or_b32_e32 v181, 3, v158
	v_or_b32_e32 v182, 8, v158
	v_or_b32_e32 v183, 9, v158
	v_or_b32_e32 v184, 10, v158
	v_or_b32_e32 v185, 11, v158
	v_or_b32_e32 v186, 16, v158
	v_or_b32_e32 v187, 17, v158
	v_or_b32_e32 v188, 18, v158
	v_or_b32_e32 v189, 19, v158
	v_or_b32_e32 v190, 24, v158
	v_or_b32_e32 v191, 25, v158
	v_or_b32_e32 v192, 26, v158
	v_or_b32_e32 v193, 27, v158
	v_lshl_add_u64 v[44:45], s[20:21], 0, v[34:35]
	s_movk_i32 s33, 0x2c00
	s_lshl_b32 s46, s2, 6
	s_lshl_b32 s47, s84, 6
	v_add3_u32 v194, v3, v0, 0
	s_mov_b32 s8, 0x3a800000
	s_mov_b32 s52, 0x800000
	s_mov_b64 s[42:43], 0xb000
	v_mov_b32_e32 v195, 0x160000
	s_mov_b32 s53, s2
	v_readlane_b32 s69, v249, 32

; __device__ __forceinline__ float bf1(bf16 h) { return __uint_as_float((unsigned)h << 16); }
; __device__ __forceinline__ unsigned pk2(float lo, float hi) { return pg8::cvt_pk_bf16(lo, hi); }
; __device__ __forceinline__ bf16 f2bf(float f) { return (bf16)(pg8::cvt_pk_bf16(f, 0.f) & 0xffffu); }
; __global__ void __launch_bounds__(NT, 2) mk_fwd(Args args) {
;     ...
;                     const float* wrow = wsp + ((size_t)h * 128 + it_ * 32 + (lane & 31)) * 128 + (lane >> 5) * 8;
; #pragma unroll 2
;                     for (int ks = 0; ks < nks; ++ks) {
;                         const f32x4 w0 = *(const f32x4*)(wrow + ks * 16), w1 = *(const f32x4*)(wrow + ks * 16 + 4);
;                         u32x4 au; au.x = pk2(w0.x, w0.y); au.y = pk2(w0.z, w0.w); au.z = pk2(w1.x, w1.y); au.w = pk2(w1.z, w1.w);
;                         const bf16x8 af = __builtin_bit_cast(bf16x8, au);
; #pragma unroll
;                         for (int q = 0; q < 2; ++q) { const bf16x8 bfr = *(const bf16x8*)(VnT + ((dt0 + q) * 32 + (lane & 31)) * 136 + ks * 16 + (lane >> 5) * 8);
;                             acc[q] = __builtin_amdgcn_mfma_f32_32x32x16_bf16(af, bfr, acc[q], 0, 0, 0); }
;                     }
; #pragma unroll
;                     for (int q = 0; q < 2; ++q)
; #pragma unroll
;                         for (int r = 0; r < 16; ++r) { const int i = it_ * 32 + (r & 3) + 8 * (r >> 2) + 4 * (lane >> 5), d = (dt0 + q) * 32 + (lane & 31);
;                             const float z = acc[q][r] + bs[h * 128 + i];
;                             HB[(size_t)(T0 + i) * DM + h * 128 + d] = f2bf(bf1(gu[q][r]) * z); }
.LBB0_386:
	v_lshl_add_u64 v[246:247], s[6:7], 2, v[154:155]
	ds_read_b128 v[226:229], v157
	ds_read_b128 v[230:233], v157 offset:32
	global_load_dwordx4 v[234:237], v[246:247], off
	global_load_dwordx4 v[238:241], v[246:247], off offset:16
	s_add_i32 s45, s45, -2
	s_add_i32 s6, s6, 32
	s_cmp_lg_u32 s45, 0
	s_waitcnt vmcnt(1)
	v_cvt_pk_bf16_f32 v234, v234, v235
	v_cvt_pk_bf16_f32 v235, v236, v237
	s_waitcnt vmcnt(0)
	v_cvt_pk_bf16_f32 v236, v238, v239
	v_cvt_pk_bf16_f32 v237, v240, v241
	s_waitcnt lgkmcnt(1)
	v_mfma_f32_32x32x16_bf16 v[0:15], v[234:237], v[226:229], v[0:15]
	ds_read_b128 v[226:229], v157 offset:8704
	ds_read_b128 v[238:241], v157 offset:8736
	global_load_dwordx4 v[242:245], v[246:247], off offset:64
	v_add_u32_e32 v157, 64, v157
	s_waitcnt lgkmcnt(1)
	v_mfma_f32_32x32x16_bf16 v[16:31], v[234:237], v[226:229], v[16:31]
	global_load_dwordx4 v[226:229], v[246:247], off offset:80
	s_waitcnt vmcnt(1)
	v_cvt_pk_bf16_f32 v234, v242, v243
	v_cvt_pk_bf16_f32 v235, v244, v245
	s_waitcnt vmcnt(0)
	v_cvt_pk_bf16_f32 v236, v226, v227
	v_cvt_pk_bf16_f32 v237, v228, v229
	s_nop 0
	v_mfma_f32_32x32x16_bf16 v[0:15], v[234:237], v[230:233], v[0:15]
	s_waitcnt lgkmcnt(0)
	v_mfma_f32_32x32x16_bf16 v[16:31], v[234:237], v[238:241], v[16:31]
	s_cbranch_scc1 .LBB0_386
	v_add_u32_e32 v154, s44, v158
	v_ashrrev_i32_e32 v155, 31, v154
	v_lshl_add_u64 v[154:155], v[154:155], 2, s[54:55]
	global_load_dword v226, v[154:155], off
	v_lshlrev_b32_e32 v227, 16, v156
	v_or_b32_e32 v156, s44, v84
	v_mov_b32_e32 v157, v39
	v_lshl_add_u64 v[156:157], v[156:157], 1, s[80:81]
	global_load_dword v238, v[154:155], off offset:12
	global_load_dword v239, v[154:155], off offset:76
	v_lshlrev_b32_e32 v245, 16, v196
	v_lshlrev_b32_e32 v241, 16, v197
	v_lshlrev_b32_e32 v242, 16, v208
	v_lshlrev_b32_e32 v243, 16, v204
	v_lshlrev_b32_e32 v244, 16, v200
	v_lshlrev_b32_e32 v246, 16, v207
	v_lshlrev_b32_e32 v247, 16, v203
	v_or_b32_e32 v230, s44, v102
	v_mov_b32_e32 v231, v103
	v_or_b32_e32 v232, s44, v106
	v_mov_b32_e32 v233, v107
	v_or_b32_e32 v234, s44, v110
	v_mov_b32_e32 v235, v111
	v_or_b32_e32 v208, s44, v114
	v_or_b32_e32 v204, s44, v118
	v_or_b32_e32 v200, s44, v122
	v_or_b32_e32 v196, s44, v126
	v_mov_b32_e32 v197, v127
	v_mov_b32_e32 v207, v139
	v_mov_b32_e32 v203, v143
	v_lshl_add_u64 v[196:197], v[196:197], 1, s[80:81]
	v_lshlrev_b32_e32 v248, 16, v199
	v_lshlrev_b32_e32 v34, 16, v34
	s_add_i32 s60, s60, 1
	v_mov_b32_e32 v199, v147
	v_or_b32_e32 v236, s44, v150
	v_mov_b32_e32 v237, v151
	s_cmp_eq_u32 s60, 4
	s_waitcnt vmcnt(2)
	v_add_f32_e32 v0, v0, v226
	v_mul_f32_e32 v0, v0, v227
	v_cvt_pk_bf16_f32 v0, v0, v35
	global_store_short v[156:157], v0, off
	global_load_dwordx2 v[156:157], v[154:155], off
	v_lshlrev_b32_e32 v0, 16, v225
	v_or_b32_e32 v226, s44, v88
	v_mov_b32_e32 v227, v41
	v_lshl_add_u64 v[226:227], v[226:227], 1, s[80:81]
	global_load_dword v228, v[154:155], off offset:32
	global_load_dword v229, v[154:155], off offset:96
	v_mov_b32_e32 v225, v85
	global_load_dword v240, v[154:155], off offset:44
	s_waitcnt vmcnt(3)
	v_add_f32_e32 v1, v1, v157
	v_mul_f32_e32 v0, v1, v0
	v_cvt_pk_bf16_f32 v0, v0, v35
	global_store_short v[226:227], v0, off
	global_load_dwordx2 v[0:1], v[154:155], off offset:4
	v_lshlrev_b32_e32 v157, 16, v224
	v_or_b32_e32 v224, s44, v92
	v_lshl_add_u64 v[224:225], v[224:225], 1, s[80:81]
	v_or_b32_e32 v226, s44, v96
	v_mov_b32_e32 v227, v89
	s_waitcnt vmcnt(4)
	v_add_f32_e32 v4, v4, v228
	v_lshl_add_u64 v[226:227], v[226:227], 1, s[80:81]
	v_or_b32_e32 v228, s44, v98
	s_waitcnt vmcnt(0)
	v_add_f32_e32 v1, v2, v1
	v_mul_f32_e32 v1, v1, v157
	v_cvt_pk_bf16_f32 v1, v1, v35
	global_store_short v[224:225], v1, off
	global_load_dwordx2 v[224:225], v[154:155], off offset:8
	v_lshlrev_b32_e32 v1, 16, v222
	global_load_dword v157, v[154:155], off offset:64
	v_lshlrev_b32_e32 v2, 16, v223
	v_or_b32_e32 v222, s44, v100
	v_mov_b32_e32 v223, v93
	v_mul_f32_e32 v2, v4, v2
	v_lshl_add_u64 v[222:223], v[222:223], 1, s[80:81]
	v_cvt_pk_bf16_f32 v2, v2, v35
	v_add_f32_e32 v0, v17, v0
	s_waitcnt vmcnt(1)
	v_add_f32_e32 v3, v3, v225
	v_mul_f32_e32 v1, v3, v1
	v_cvt_pk_bf16_f32 v1, v1, v35
	global_store_short v[226:227], v1, off
	global_store_short v[222:223], v2, off
	global_load_dwordx2 v[2:3], v[154:155], off offset:32
	v_lshlrev_b32_e32 v1, 16, v221
	v_or_b32_e32 v222, s44, v104
	v_mov_b32_e32 v223, v97
	global_load_dword v225, v[154:155], off offset:108
	v_lshl_add_u64 v[222:223], v[222:223], 1, s[80:81]
	v_mov_b32_e32 v221, v101
	v_or_b32_e32 v226, s44, v94
	v_mov_b32_e32 v227, v95
	s_waitcnt vmcnt(1)
	v_add_f32_e32 v3, v5, v3
	v_mul_f32_e32 v1, v3, v1
	v_cvt_pk_bf16_f32 v1, v1, v35
	global_store_short v[222:223], v1, off
	global_load_dwordx2 v[4:5], v[154:155], off offset:36
	v_lshlrev_b32_e32 v1, 16, v220
	v_or_b32_e32 v220, s44, v108
	v_lshl_add_u64 v[220:221], v[220:221], 1, s[80:81]
	v_or_b32_e32 v222, s44, v112
	v_mov_b32_e32 v223, v105
	v_lshl_add_u64 v[222:223], v[222:223], 1, s[80:81]
	v_add_f32_e32 v2, v20, v2
	s_waitcnt vmcnt(0)
	v_add_f32_e32 v3, v6, v5
	v_mul_f32_e32 v1, v3, v1
	v_cvt_pk_bf16_f32 v1, v1, v35
	global_store_short v[220:221], v1, off
	global_load_dwordx2 v[220:221], v[154:155], off offset:40
	v_lshlrev_b32_e32 v3, 16, v219
	v_add_f32_e32 v5, v8, v157
	v_lshlrev_b32_e32 v1, 16, v218
	v_mul_f32_e32 v3, v5, v3
	v_or_b32_e32 v218, s44, v116
	v_mov_b32_e32 v219, v109
	v_lshl_add_u64 v[218:219], v[218:219], 1, s[80:81]
	v_cvt_pk_bf16_f32 v3, v3, v35
	v_lshlrev_b32_e32 v157, 16, v209
	v_add_f32_e32 v4, v21, v4
	v_mov_b32_e32 v209, v115
	v_mul_f32_e32 v2, v2, v157
	v_lshl_add_u64 v[208:209], v[208:209], 1, s[80:81]
	v_cvt_pk_bf16_f32 v2, v2, v35
	s_waitcnt vmcnt(0)
; __device__ __forceinline__ float bf1(bf16 h) { return __uint_as_float((unsigned)h << 16); }
; __device__ __forceinline__ bf16 f2bf(float f) { return (bf16)(pg8::cvt_pk_bf16(f, 0.f) & 0xffffu); }
; __global__ void __launch_bounds__(NT, 2) mk_fwd(Args args) {
;     ...
; #pragma unroll
;                     for (int q = 0; q < 2; ++q)
; #pragma unroll
;                         for (int r = 0; r < 16; ++r) { const int i = it_ * 32 + (r & 3) + 8 * (r >> 2) + 4 * (lane >> 5), d = (dt0 + q) * 32 + (lane & 31);
;                             const float z = acc[q][r] + bs[h * 128 + i];
;                             HB[(size_t)(T0 + i) * DM + h * 128 + d] = f2bf(bf1(gu[q][r]) * z); }
;                 }
;             }
;         }
	v_add_f32_e32 v5, v7, v221
	v_mul_f32_e32 v1, v5, v1
	v_cvt_pk_bf16_f32 v1, v1, v35
	global_store_short v[222:223], v1, off
	global_store_short v[218:219], v3, off
	global_load_dwordx2 v[6:7], v[154:155], off offset:64
	v_lshlrev_b32_e32 v1, 16, v217
	v_or_b32_e32 v218, s44, v120
	v_mov_b32_e32 v219, v113
	v_lshl_add_u64 v[218:219], v[218:219], 1, s[80:81]
	v_mov_b32_e32 v217, v117
	v_add_f32_e32 v5, v12, v229
	v_lshlrev_b32_e32 v221, 16, v201
	v_or_b32_e32 v222, s44, v90
	v_mov_b32_e32 v223, v91
	v_mov_b32_e32 v229, v99
	v_mov_b32_e32 v201, v123
	v_lshl_add_u64 v[200:201], v[200:201], 1, s[80:81]
	s_waitcnt vmcnt(0)
	v_add_f32_e32 v3, v9, v7
	v_mul_f32_e32 v1, v3, v1
	v_cvt_pk_bf16_f32 v1, v1, v35
	global_store_short v[218:219], v1, off
	global_load_dwordx2 v[8:9], v[154:155], off offset:68
	v_lshlrev_b32_e32 v1, 16, v216
	v_or_b32_e32 v216, s44, v124
	v_lshl_add_u64 v[216:217], v[216:217], 1, s[80:81]
	v_or_b32_e32 v218, s44, v136
	v_mov_b32_e32 v219, v121
	v_lshl_add_u64 v[218:219], v[218:219], 1, s[80:81]
	v_lshlrev_b32_e32 v7, 16, v206
	v_mul_f32_e32 v0, v0, v7
	v_add_f32_e32 v6, v24, v6
	v_or_b32_e32 v206, s44, v138
	v_cvt_pk_bf16_f32 v0, v0, v35
	v_mul_f32_e32 v6, v6, v242
	v_lshl_add_u64 v[206:207], v[206:207], 1, s[80:81]
	v_cvt_pk_bf16_f32 v6, v6, v35
	s_waitcnt vmcnt(0)
	v_add_f32_e32 v3, v10, v9
	v_mul_f32_e32 v1, v3, v1
	v_cvt_pk_bf16_f32 v1, v1, v35
	global_store_short v[216:217], v1, off
	global_load_dwordx2 v[216:217], v[154:155], off offset:72
	v_lshlrev_b32_e32 v3, 16, v215
	v_lshlrev_b32_e32 v1, 16, v214
	v_mul_f32_e32 v3, v5, v3
	v_or_b32_e32 v214, s44, v140
	v_mov_b32_e32 v215, v125
	v_lshl_add_u64 v[214:215], v[214:215], 1, s[80:81]
	v_cvt_pk_bf16_f32 v3, v3, v35
	v_lshlrev_b32_e32 v9, 16, v202
	v_add_f32_e32 v8, v25, v8
	v_or_b32_e32 v202, s44, v142
	v_mul_f32_e32 v8, v8, v243
	v_lshl_add_u64 v[202:203], v[202:203], 1, s[80:81]
	v_cvt_pk_bf16_f32 v8, v8, v35
	s_waitcnt vmcnt(0)
	v_add_f32_e32 v5, v11, v217
	v_mul_f32_e32 v1, v5, v1
	v_cvt_pk_bf16_f32 v1, v1, v35
	global_store_short v[218:219], v1, off
	global_store_short v[214:215], v3, off
	global_load_dwordx2 v[10:11], v[154:155], off offset:96
	v_lshlrev_b32_e32 v1, 16, v213
	v_or_b32_e32 v214, s44, v144
	v_mov_b32_e32 v215, v129
	v_lshl_add_u64 v[214:215], v[214:215], 1, s[80:81]
	v_mov_b32_e32 v213, v131
	v_lshlrev_b32_e32 v5, 16, v210
	v_or_b32_e32 v210, s44, v82
	v_lshlrev_b32_e32 v217, 16, v205
	v_or_b32_e32 v218, s44, v86
	v_mov_b32_e32 v219, v87
	v_mov_b32_e32 v205, v119
	v_mul_f32_e32 v4, v4, v217
	v_lshl_add_u64 v[204:205], v[204:205], 1, s[80:81]
	v_cvt_pk_bf16_f32 v4, v4, v35
	s_waitcnt vmcnt(0)
	v_add_f32_e32 v3, v13, v11
	v_mul_f32_e32 v1, v3, v1
	v_cvt_pk_bf16_f32 v1, v1, v35
	global_store_short v[214:215], v1, off
	global_load_dwordx2 v[12:13], v[154:155], off offset:100
	v_lshlrev_b32_e32 v1, 16, v212
	v_or_b32_e32 v212, s44, v148
	v_lshl_add_u64 v[212:213], v[212:213], 1, s[80:81]
	v_lshlrev_b32_e32 v11, 16, v198
	v_lshlrev_b32_e32 v3, 16, v211
	v_mov_b32_e32 v211, v83
	v_add_f32_e32 v10, v28, v10
	v_or_b32_e32 v214, s44, v152
	v_mov_b32_e32 v215, v133
	v_lshl_add_u64 v[210:211], v[210:211], 1, s[80:81]
	v_mul_f32_e32 v10, v10, v246
	v_cvt_pk_bf16_f32 v10, v10, v35
	v_or_b32_e32 v198, s44, v146
	v_lshl_add_u64 v[198:199], v[198:199], 1, s[80:81]
	s_waitcnt vmcnt(0)
	v_add_f32_e32 v13, v14, v13
	v_mul_f32_e32 v1, v13, v1
	v_cvt_pk_bf16_f32 v1, v1, v35
	global_store_short v[212:213], v1, off
	global_load_dwordx2 v[154:155], v[154:155], off offset:104
	v_add_f32_e32 v1, v19, v238
	v_add_f32_e32 v13, v27, v239
	v_mul_f32_e32 v1, v1, v11
	v_mul_f32_e32 v11, v13, v245
	v_add_f32_e32 v13, v16, v156
	v_mul_f32_e32 v5, v13, v5
	v_add_f32_e32 v13, v23, v240
	v_mul_f32_e32 v7, v13, v241
	v_add_f32_e32 v13, v18, v224
	v_add_f32_e32 v14, v22, v220
	v_add_f32_e32 v16, v26, v216
	v_add_f32_e32 v12, v29, v12
	v_cvt_pk_bf16_f32 v5, v5, v35
	v_mul_f32_e32 v9, v13, v9
	v_mul_f32_e32 v14, v14, v221
	v_mul_f32_e32 v16, v16, v244
	v_mul_f32_e32 v12, v12, v247
	v_lshl_add_u64 v[212:213], v[214:215], 1, s[80:81]
	v_lshl_add_u64 v[214:215], v[218:219], 1, s[80:81]
	v_lshl_add_u64 v[218:219], v[222:223], 1, s[80:81]
	v_lshl_add_u64 v[222:223], v[226:227], 1, s[80:81]
	v_lshl_add_u64 v[226:227], v[228:229], 1, s[80:81]
	v_lshl_add_u64 v[228:229], v[230:231], 1, s[80:81]
	v_lshl_add_u64 v[230:231], v[232:233], 1, s[80:81]
	v_lshl_add_u64 v[232:233], v[234:235], 1, s[80:81]
	v_cvt_pk_bf16_f32 v1, v1, v35
	v_cvt_pk_bf16_f32 v11, v11, v35
	v_cvt_pk_bf16_f32 v7, v7, v35
	v_cvt_pk_bf16_f32 v9, v9, v35
	v_cvt_pk_bf16_f32 v14, v14, v35
	v_cvt_pk_bf16_f32 v16, v16, v35
	v_cvt_pk_bf16_f32 v12, v12, v35
	global_store_short v[210:211], v5, off
	global_store_short v[214:215], v0, off
	global_store_short v[218:219], v9, off
	global_store_short v[222:223], v1, off
	global_store_short v[226:227], v2, off
	global_store_short v[228:229], v4, off
	global_store_short v[230:231], v14, off
	global_store_short v[232:233], v7, off
	global_store_short v[208:209], v6, off
	global_store_short v[204:205], v8, off
	global_store_short v[200:201], v16, off
	global_store_short v[196:197], v11, off
	global_store_short v[206:207], v10, off
	global_store_short v[202:203], v12, off
	v_add_f32_e32 v13, v31, v225
	v_mul_f32_e32 v13, v13, v34
	v_lshl_add_u64 v[234:235], v[236:237], 1, s[80:81]
	v_cvt_pk_bf16_f32 v13, v13, v35
	s_waitcnt vmcnt(14)
	v_add_f32_e32 v0, v15, v155
	v_add_f32_e32 v1, v30, v154
	v_mul_f32_e32 v0, v0, v3
	v_mul_f32_e32 v1, v1, v248
	v_cvt_pk_bf16_f32 v0, v0, v35
	v_cvt_pk_bf16_f32 v1, v1, v35
	global_store_short v[212:213], v0, off
	global_store_short v[198:199], v1, off
	global_store_short v[234:235], v13, off
	s_cbranch_scc0 .LBB0_385
	s_add_i32 s53, s53, s84
	s_add_i32 s46, s46, s47
	s_cmpk_gt_i32 s53, 0xff
	s_cbranch_scc0 .LBB0_374
	s_cmp_eq_u32 s101, 1
	s_cbranch_scc0 .LBB0_389
	s_mov_b32 s101, 2
	s_mov_b32 s58, s98
	s_mov_b32 s59, s99
	s_mov_b32 s60, s100
	s_branch .Lp3_preA
